# grid barrier moved from after phase 5 to after phase 6 (phase 6 independent of phase 5)
# baseline (speedup 1.0000x reference)
; __global__ void __launch_bounds__(NWAVES * 64, 2) fwd_megakernel(Args args) {
;     ...
;         if (j != 2 && j != 6) xcd_barrier(xbar);
.LBB0_643:
	s_cmp_eq_u32 s39, 2
	s_cbranch_scc1 .LBB0_215
	s_cmp_eq_u32 s39, 5
	s_cbranch_scc1 .LBB0_215
	s_branch .LBB0_853

; #define PG8_WAIT_V(n) asm volatile("s_waitcnt vmcnt(" #n ")" ::: "memory")
; #define PG8_BAR __builtin_amdgcn_s_barrier()
; __device__ __forceinline__ void gemm_phase(LAS unsigned char* lds, const Gemm g, const StaticOrder& S, const Epi& E) {
;     ...
;     PG8_WAIT_V(0);
;     PG8_BAR;
; __global__ void __launch_bounds__(NWAVES * 64, 2) fwd_megakernel(Args args) {
;     ...
;         if (j != 2 && j != 6) xcd_barrier(xbar);
.LBB0_852:
	s_waitcnt vmcnt(0)
	v_readlane_b32 s72, v250, 34
	v_readlane_b32 s94, v248, 29
	v_readlane_b32 s48, v248, 22
	v_readlane_b32 s30, v248, 26
	v_readlane_b32 s73, v250, 35
	s_mov_b32 s47, s6
	s_mov_b32 s68, s7
	v_readlane_b32 s76, v248, 28
	v_readlane_b32 s95, v248, 30
	v_readlane_b32 s49, v248, 23
	v_readlane_b32 s77, v248, 31
	v_readlane_b32 s88, v248, 32
	v_readlane_b32 s21, v248, 24
	v_readlane_b32 s24, v248, 25
	v_readlane_b32 s31, v248, 27
	s_mov_b32 s25, 0x7f800000
	s_mov_b32 s26, 0x3f2aaaab
	s_mov_b32 s28, 0x3f317218
	s_mov_b32 s38, 0x33800000
	v_readlane_b32 s39, v248, 33
	s_mov_b32 s46, 0xbfb8aa3b
	s_barrier
	s_cmp_eq_u32 s39, 2
	s_cbranch_scc1 .LBB0_215
	s_cmp_eq_u32 s39, 5
	s_cbranch_scc1 .LBB0_215
